# static s_setprio 1 for waves 0-3 (the other half) during the SSD/LRU/HGRN scan phases
# speedup vs baseline: 1.0116x; 1.0027x over previous
; __device__ __forceinline__ void ssd_phase(const Args& A, unsigned char* smem, const bool dry) {
;     ...
;     for (int u = blockIdx.x; u < 256; u += gridDim.x) {
;         const int b = u >> 4, h = u & 15, g = h >> 2;
;         __syncthreads();
.LBB0_415:
	v_readfirstlane_b32 s98, v152
	s_nop 3
	s_cmp_lt_u32 s98, 0x100
	s_cbranch_scc0 .Lsp0_skip
	s_setprio 1
